# SwiGLU core as a hand software pipeline over the 32 pair chains: trans and plain VALU alternate, no hazard nops
# baseline (speedup 1.0000x reference)
; DI unsigned pk2(float lo, float hi) { return pg8::cvt_pk_bf16(lo, hi); }
;     DI void operator()(const f32x4 (&acc)[2][2][4][2], const pg8::Unit& u, int wr, int wc, int fr, int fq) const {
;     ...
; #pragma unroll
;         for (int ai = 0; ai < 2; ++ai)
; #pragma unroll
;             for (int m = 0; m < 4; ++m) {
;                 typedef float f32x2 __attribute__((ext_vector_type(2)));
;                 const float r = rs[ai][m]; const float r2s = r * r, rls = r * -1.44269504f; const f32x2 r2 = {r2s, r2s}, rl = {rls, rls};
;                 unsigned hw[4];
; #pragma unroll
;                 for (int q = 0; q < 4; ++q) {
;                     const f32x4 gq = acc[ai][0][m][q >> 1], uq = acc[ai][1][m][q >> 1];
;                     const f32x2 g2 = {gq[2 * (q & 1)], gq[2 * (q & 1) + 1]}, u2 = {uq[2 * (q & 1)], uq[2 * (q & 1) + 1]};
;                     const f32x2 t = g2 * rl; f32x2 e; e.x = __builtin_amdgcn_exp2f(t.x); e.y = __builtin_amdgcn_exp2f(t.y);
;                     const f32x2 d = e + 1.0f; f32x2 rc; rc.x = __builtin_amdgcn_rcpf(d.x); rc.y = __builtin_amdgcn_rcpf(d.y);
;                     const f32x2 hv = ((g2 * u2) * r2) * rc;
;                     hw[q] = pk2(hv.x, hv.y);
;                 }
;                 u32x4 w; w.x = hw[0]; w.y = hw[1]; w.z = hw[2]; w.w = hw[3];
;                 *(u32x4*)(H + (size_t)(row0 + ai * 128 + m * 16) * DFF + col0) = w;
.Lrc_done_0:
	v_mov_b64_e32 v[236:237], s[84:85]
	v_lshlrev_b64 v[180:181], 1, v[162:163]
	v_mul_f32_e32 v178, 0xbfb8aa3b, v161
	v_pk_mul_f32 v[126:127], v[126:127], v[178:179] op_sel_hi:[1,0]
	v_mul_f32_e32 v132, v161, v161
	v_pk_mul_f32 v[122:123], v[122:123], v[132:133] op_sel_hi:[1,0]
	v_exp_f32_e32 v126, v126
	v_pk_mul_f32 v[128:129], v[128:129], v[178:179] op_sel_hi:[1,0]
	v_exp_f32_e32 v127, v127
	s_nop 0
	v_pk_add_f32 v[126:127], v[126:127], 1.0 op_sel_hi:[1,0]
	v_pk_mul_f32 v[124:125], v[124:125], v[132:133] op_sel_hi:[1,0]
	v_exp_f32_e32 v128, v128
	v_pk_mul_f32 v[118:119], v[118:119], v[178:179] op_sel_hi:[1,0]
	v_exp_f32_e32 v129, v129
	v_rcp_f32_e32 v126, v126
	v_pk_add_f32 v[128:129], v[128:129], 1.0 op_sel_hi:[1,0]
	v_rcp_f32_e32 v127, v127
	v_pk_mul_f32 v[114:115], v[114:115], v[132:133] op_sel_hi:[1,0]
	v_exp_f32_e32 v118, v118
	v_pk_mul_f32 v[120:121], v[120:121], v[178:179] op_sel_hi:[1,0]
	v_exp_f32_e32 v119, v119
	v_pk_mul_f32 v[122:123], v[122:123], v[126:127]
	v_rcp_f32_e32 v128, v128
	v_pk_add_f32 v[118:119], v[118:119], 1.0 op_sel_hi:[1,0]
	v_rcp_f32_e32 v129, v129
	v_pk_mul_f32 v[116:117], v[116:117], v[132:133] op_sel_hi:[1,0]
	v_exp_f32_e32 v120, v120
	v_mul_f32_e32 v190, 0xbfb8aa3b, v159
	v_pk_mul_f32 v[110:111], v[110:111], v[190:191] op_sel_hi:[1,0]
	v_exp_f32_e32 v121, v121
	v_cvt_pk_bf16_f32 v126, v122, v123
	v_pk_mul_f32 v[124:125], v[124:125], v[128:129]
	v_rcp_f32_e32 v118, v118
	v_pk_add_f32 v[120:121], v[120:121], 1.0 op_sel_hi:[1,0]
	v_rcp_f32_e32 v119, v119
	v_mul_f32_e32 v234, v159, v159
	v_pk_mul_f32 v[106:107], v[106:107], v[234:235] op_sel_hi:[1,0]
	v_exp_f32_e32 v110, v110
	v_pk_mul_f32 v[112:113], v[112:113], v[190:191] op_sel_hi:[1,0]
	v_exp_f32_e32 v111, v111
	v_cvt_pk_bf16_f32 v127, v124, v125
	v_pk_mul_f32 v[114:115], v[114:115], v[118:119]
	v_rcp_f32_e32 v120, v120
	v_pk_add_f32 v[110:111], v[110:111], 1.0 op_sel_hi:[1,0]
	v_rcp_f32_e32 v121, v121
	v_pk_mul_f32 v[108:109], v[108:109], v[234:235] op_sel_hi:[1,0]
	v_exp_f32_e32 v112, v112
	v_pk_mul_f32 v[102:103], v[102:103], v[190:191] op_sel_hi:[1,0]
	v_exp_f32_e32 v113, v113
	v_cvt_pk_bf16_f32 v128, v114, v115
	v_pk_mul_f32 v[116:117], v[116:117], v[120:121]
	v_rcp_f32_e32 v110, v110
	v_pk_add_f32 v[112:113], v[112:113], 1.0 op_sel_hi:[1,0]
	v_rcp_f32_e32 v111, v111
	v_pk_mul_f32 v[98:99], v[98:99], v[234:235] op_sel_hi:[1,0]
	v_exp_f32_e32 v102, v102
	v_pk_mul_f32 v[104:105], v[104:105], v[190:191] op_sel_hi:[1,0]
	v_exp_f32_e32 v103, v103
	v_cvt_pk_bf16_f32 v129, v116, v117
	v_mad_i64_i32 v[118:119], s[2:3], v160, s27, v[236:237]
	v_lshl_add_u64 v[118:119], v[118:119], 0, v[180:181]
	global_store_dwordx4 v[118:119], v[126:129], off
	v_pk_mul_f32 v[106:107], v[106:107], v[110:111]
	v_rcp_f32_e32 v112, v112
	v_pk_add_f32 v[102:103], v[102:103], 1.0 op_sel_hi:[1,0]
	v_rcp_f32_e32 v113, v113
	v_pk_mul_f32 v[100:101], v[100:101], v[234:235] op_sel_hi:[1,0]
	v_exp_f32_e32 v104, v104
	v_mul_f32_e32 v178, 0xbfb8aa3b, v157
	v_pk_mul_f32 v[94:95], v[94:95], v[178:179] op_sel_hi:[1,0]
	v_exp_f32_e32 v105, v105
	v_cvt_pk_bf16_f32 v110, v106, v107
	v_pk_mul_f32 v[108:109], v[108:109], v[112:113]
	v_rcp_f32_e32 v102, v102
	v_pk_add_f32 v[104:105], v[104:105], 1.0 op_sel_hi:[1,0]
	v_rcp_f32_e32 v103, v103
	v_mul_f32_e32 v132, v157, v157
	v_pk_mul_f32 v[90:91], v[90:91], v[132:133] op_sel_hi:[1,0]
	v_exp_f32_e32 v94, v94
	v_pk_mul_f32 v[96:97], v[96:97], v[178:179] op_sel_hi:[1,0]
	v_exp_f32_e32 v95, v95
	v_cvt_pk_bf16_f32 v111, v108, v109
	v_pk_mul_f32 v[98:99], v[98:99], v[102:103]
	v_rcp_f32_e32 v104, v104
	v_pk_add_f32 v[94:95], v[94:95], 1.0 op_sel_hi:[1,0]
	v_rcp_f32_e32 v105, v105
	v_pk_mul_f32 v[92:93], v[92:93], v[132:133] op_sel_hi:[1,0]
	v_exp_f32_e32 v96, v96
	v_pk_mul_f32 v[86:87], v[86:87], v[178:179] op_sel_hi:[1,0]
	v_exp_f32_e32 v97, v97
	v_cvt_pk_bf16_f32 v112, v98, v99
	v_pk_mul_f32 v[100:101], v[100:101], v[104:105]
	v_rcp_f32_e32 v94, v94
	v_pk_add_f32 v[96:97], v[96:97], 1.0 op_sel_hi:[1,0]
	v_rcp_f32_e32 v95, v95
	v_pk_mul_f32 v[82:83], v[82:83], v[132:133] op_sel_hi:[1,0]
	v_exp_f32_e32 v86, v86
	v_pk_mul_f32 v[88:89], v[88:89], v[178:179] op_sel_hi:[1,0]
	v_exp_f32_e32 v87, v87
	v_cvt_pk_bf16_f32 v113, v100, v101
	v_mad_i64_i32 v[102:103], s[2:3], v158, s27, v[236:237]
	v_lshl_add_u64 v[102:103], v[102:103], 0, v[180:181]
	global_store_dwordx4 v[102:103], v[110:113], off
	v_pk_mul_f32 v[90:91], v[90:91], v[94:95]
	v_rcp_f32_e32 v96, v96
	v_pk_add_f32 v[86:87], v[86:87], 1.0 op_sel_hi:[1,0]
	v_rcp_f32_e32 v97, v97
	v_pk_mul_f32 v[84:85], v[84:85], v[132:133] op_sel_hi:[1,0]
	v_exp_f32_e32 v88, v88
	v_mul_f32_e32 v190, 0xbfb8aa3b, v155
	v_pk_mul_f32 v[78:79], v[78:79], v[190:191] op_sel_hi:[1,0]
	v_exp_f32_e32 v89, v89
	v_cvt_pk_bf16_f32 v94, v90, v91
	v_pk_mul_f32 v[92:93], v[92:93], v[96:97]
	v_rcp_f32_e32 v86, v86
	v_pk_add_f32 v[88:89], v[88:89], 1.0 op_sel_hi:[1,0]
	v_rcp_f32_e32 v87, v87
	v_mul_f32_e32 v234, v155, v155
	v_pk_mul_f32 v[74:75], v[74:75], v[234:235] op_sel_hi:[1,0]
	v_exp_f32_e32 v78, v78
	v_pk_mul_f32 v[80:81], v[80:81], v[190:191] op_sel_hi:[1,0]
	v_exp_f32_e32 v79, v79
	v_cvt_pk_bf16_f32 v95, v92, v93
	v_pk_mul_f32 v[82:83], v[82:83], v[86:87]
	v_rcp_f32_e32 v88, v88
	v_pk_add_f32 v[78:79], v[78:79], 1.0 op_sel_hi:[1,0]
	v_rcp_f32_e32 v89, v89
	v_pk_mul_f32 v[76:77], v[76:77], v[234:235] op_sel_hi:[1,0]
	v_exp_f32_e32 v80, v80
	v_pk_mul_f32 v[70:71], v[70:71], v[190:191] op_sel_hi:[1,0]
	v_exp_f32_e32 v81, v81
	v_cvt_pk_bf16_f32 v96, v82, v83
	v_pk_mul_f32 v[84:85], v[84:85], v[88:89]
	v_rcp_f32_e32 v78, v78
	v_pk_add_f32 v[80:81], v[80:81], 1.0 op_sel_hi:[1,0]
	v_rcp_f32_e32 v79, v79
; DI unsigned pk2(float lo, float hi) { return pg8::cvt_pk_bf16(lo, hi); }
;     DI void operator()(const f32x4 (&acc)[2][2][4][2], const pg8::Unit& u, int wr, int wc, int fr, int fq) const {
;     ...
; #pragma unroll
;         for (int ai = 0; ai < 2; ++ai)
; #pragma unroll
;             for (int m = 0; m < 4; ++m) {
;                 typedef float f32x2 __attribute__((ext_vector_type(2)));
;                 const float r = rs[ai][m]; const float r2s = r * r, rls = r * -1.44269504f; const f32x2 r2 = {r2s, r2s}, rl = {rls, rls};
;                 unsigned hw[4];
; #pragma unroll
;                 for (int q = 0; q < 4; ++q) {
;                     const f32x4 gq = acc[ai][0][m][q >> 1], uq = acc[ai][1][m][q >> 1];
;                     const f32x2 g2 = {gq[2 * (q & 1)], gq[2 * (q & 1) + 1]}, u2 = {uq[2 * (q & 1)], uq[2 * (q & 1) + 1]};
;                     const f32x2 t = g2 * rl; f32x2 e; e.x = __builtin_amdgcn_exp2f(t.x); e.y = __builtin_amdgcn_exp2f(t.y);
;                     const f32x2 d = e + 1.0f; f32x2 rc; rc.x = __builtin_amdgcn_rcpf(d.x); rc.y = __builtin_amdgcn_rcpf(d.y);
;                     const f32x2 hv = ((g2 * u2) * r2) * rc;
;                     hw[q] = pk2(hv.x, hv.y);
;                 }
;                 u32x4 w; w.x = hw[0]; w.y = hw[1]; w.z = hw[2]; w.w = hw[3];
;                 *(u32x4*)(H + (size_t)(row0 + ai * 128 + m * 16) * DFF + col0) = w;
	v_pk_mul_f32 v[66:67], v[66:67], v[234:235] op_sel_hi:[1,0]
	v_exp_f32_e32 v70, v70
	v_pk_mul_f32 v[72:73], v[72:73], v[190:191] op_sel_hi:[1,0]
	v_exp_f32_e32 v71, v71
	v_cvt_pk_bf16_f32 v97, v84, v85
	v_mad_i64_i32 v[86:87], s[2:3], v156, s27, v[236:237]
	v_lshl_add_u64 v[86:87], v[86:87], 0, v[180:181]
	global_store_dwordx4 v[86:87], v[94:97], off
	v_pk_mul_f32 v[74:75], v[74:75], v[78:79]
	v_rcp_f32_e32 v80, v80
	v_pk_add_f32 v[70:71], v[70:71], 1.0 op_sel_hi:[1,0]
	v_rcp_f32_e32 v81, v81
	v_pk_mul_f32 v[68:69], v[68:69], v[234:235] op_sel_hi:[1,0]
	v_exp_f32_e32 v72, v72
	v_mul_f32_e32 v178, 0xbfb8aa3b, v153
	v_pk_mul_f32 v[62:63], v[62:63], v[178:179] op_sel_hi:[1,0]
	v_exp_f32_e32 v73, v73
	v_cvt_pk_bf16_f32 v78, v74, v75
	v_pk_mul_f32 v[76:77], v[76:77], v[80:81]
	v_rcp_f32_e32 v70, v70
	v_pk_add_f32 v[72:73], v[72:73], 1.0 op_sel_hi:[1,0]
	v_rcp_f32_e32 v71, v71
	v_mul_f32_e32 v132, v153, v153
	v_pk_mul_f32 v[58:59], v[58:59], v[132:133] op_sel_hi:[1,0]
	v_exp_f32_e32 v62, v62
	v_pk_mul_f32 v[64:65], v[64:65], v[178:179] op_sel_hi:[1,0]
	v_exp_f32_e32 v63, v63
	v_cvt_pk_bf16_f32 v79, v76, v77
	v_pk_mul_f32 v[66:67], v[66:67], v[70:71]
	v_rcp_f32_e32 v72, v72
	v_pk_add_f32 v[62:63], v[62:63], 1.0 op_sel_hi:[1,0]
	v_rcp_f32_e32 v73, v73
	v_pk_mul_f32 v[60:61], v[60:61], v[132:133] op_sel_hi:[1,0]
	v_exp_f32_e32 v64, v64
	v_pk_mul_f32 v[54:55], v[54:55], v[178:179] op_sel_hi:[1,0]
	v_exp_f32_e32 v65, v65
	v_cvt_pk_bf16_f32 v80, v66, v67
	v_pk_mul_f32 v[68:69], v[68:69], v[72:73]
	v_rcp_f32_e32 v62, v62
	v_pk_add_f32 v[64:65], v[64:65], 1.0 op_sel_hi:[1,0]
	v_rcp_f32_e32 v63, v63
	v_pk_mul_f32 v[50:51], v[50:51], v[132:133] op_sel_hi:[1,0]
	v_exp_f32_e32 v54, v54
	v_pk_mul_f32 v[56:57], v[56:57], v[178:179] op_sel_hi:[1,0]
	v_exp_f32_e32 v55, v55
	v_cvt_pk_bf16_f32 v81, v68, v69
	v_mad_i64_i32 v[70:71], s[2:3], v154, s27, v[236:237]
	v_lshl_add_u64 v[70:71], v[70:71], 0, v[180:181]
	global_store_dwordx4 v[70:71], v[78:81], off
	v_pk_mul_f32 v[58:59], v[58:59], v[62:63]
	v_rcp_f32_e32 v64, v64
	v_pk_add_f32 v[54:55], v[54:55], 1.0 op_sel_hi:[1,0]
	v_rcp_f32_e32 v65, v65
	v_pk_mul_f32 v[52:53], v[52:53], v[132:133] op_sel_hi:[1,0]
	v_exp_f32_e32 v56, v56
	v_mul_f32_e32 v190, 0xbfb8aa3b, v151
	v_pk_mul_f32 v[46:47], v[46:47], v[190:191] op_sel_hi:[1,0]
	v_exp_f32_e32 v57, v57
	v_cvt_pk_bf16_f32 v62, v58, v59
	v_pk_mul_f32 v[60:61], v[60:61], v[64:65]
	v_rcp_f32_e32 v54, v54
	v_pk_add_f32 v[56:57], v[56:57], 1.0 op_sel_hi:[1,0]
	v_rcp_f32_e32 v55, v55
	v_mul_f32_e32 v234, v151, v151
	v_pk_mul_f32 v[42:43], v[42:43], v[234:235] op_sel_hi:[1,0]
	v_exp_f32_e32 v46, v46
	v_pk_mul_f32 v[48:49], v[48:49], v[190:191] op_sel_hi:[1,0]
	v_exp_f32_e32 v47, v47
	v_cvt_pk_bf16_f32 v63, v60, v61
	v_pk_mul_f32 v[50:51], v[50:51], v[54:55]
	v_rcp_f32_e32 v56, v56
	v_pk_add_f32 v[46:47], v[46:47], 1.0 op_sel_hi:[1,0]
	v_rcp_f32_e32 v57, v57
	v_pk_mul_f32 v[44:45], v[44:45], v[234:235] op_sel_hi:[1,0]
	v_exp_f32_e32 v48, v48
	v_pk_mul_f32 v[38:39], v[38:39], v[190:191] op_sel_hi:[1,0]
	v_exp_f32_e32 v49, v49
	v_cvt_pk_bf16_f32 v64, v50, v51
	v_pk_mul_f32 v[52:53], v[52:53], v[56:57]
	v_rcp_f32_e32 v46, v46
	v_pk_add_f32 v[48:49], v[48:49], 1.0 op_sel_hi:[1,0]
	v_rcp_f32_e32 v47, v47
	v_pk_mul_f32 v[34:35], v[34:35], v[234:235] op_sel_hi:[1,0]
	v_exp_f32_e32 v38, v38
	v_pk_mul_f32 v[40:41], v[40:41], v[190:191] op_sel_hi:[1,0]
	v_exp_f32_e32 v39, v39
	v_cvt_pk_bf16_f32 v65, v52, v53
	v_mad_i64_i32 v[54:55], s[2:3], v152, s27, v[236:237]
	v_lshl_add_u64 v[54:55], v[54:55], 0, v[180:181]
	global_store_dwordx4 v[54:55], v[62:65], off
	v_pk_mul_f32 v[42:43], v[42:43], v[46:47]
	v_rcp_f32_e32 v48, v48
	v_pk_add_f32 v[38:39], v[38:39], 1.0 op_sel_hi:[1,0]
	v_rcp_f32_e32 v49, v49
	v_pk_mul_f32 v[36:37], v[36:37], v[234:235] op_sel_hi:[1,0]
	v_exp_f32_e32 v40, v40
	v_mul_f32_e32 v178, 0xbfb8aa3b, v131
; #define PG8_BAR __builtin_amdgcn_s_barrier()
; DI unsigned pk2(float lo, float hi) { return pg8::cvt_pk_bf16(lo, hi); }
; template <class Epi, class Sched, bool ALIGN_EPI = false, bool SP2 = false>
; __device__ __forceinline__ void gemm_phase(PG8_LAS unsigned char* lds, const Gemm g, const Sched& S, const Epi& E) {
;     ...
;         if constexpr (ALIGN_EPI) { if (wr == 0) PG8_BAR; }
;         if constexpr (!Epi::AFTER_DRAIN) { E(acc, cur, wr, wc, fr, fq); S.done(cur); }
;         if (!has_next) break;
; #pragma unroll
;         for (int a = 0; a < 2; ++a)
; #pragma unroll
;             for (int b = 0; b < 2; ++b)
; #pragma unroll
;                 for (int m = 0; m < 4; ++m)
; #pragma unroll
;                     for (int n = 0; n < 2; ++n) acc[a][b][m][n] = (f32x4){0.f, 0.f, 0.f, 0.f};
;         cur = nxt; cA = nA; cB = nB; ++ui;
;         if constexpr (ALIGN_EPI) { if (wr == 1) PG8_BAR; }
;     DI void operator()(const f32x4 (&acc)[2][2][4][2], const pg8::Unit& u, int wr, int wc, int fr, int fq) const {
;     ...
; #pragma unroll
;         for (int ai = 0; ai < 2; ++ai)
; #pragma unroll
;             for (int m = 0; m < 4; ++m) {
;                 typedef float f32x2 __attribute__((ext_vector_type(2)));
;                 const float r = rs[ai][m]; const float r2s = r * r, rls = r * -1.44269504f; const f32x2 r2 = {r2s, r2s}, rl = {rls, rls};
;                 unsigned hw[4];
; #pragma unroll
;                 for (int q = 0; q < 4; ++q) {
;                     const f32x4 gq = acc[ai][0][m][q >> 1], uq = acc[ai][1][m][q >> 1];
;                     const f32x2 g2 = {gq[2 * (q & 1)], gq[2 * (q & 1) + 1]}, u2 = {uq[2 * (q & 1)], uq[2 * (q & 1) + 1]};
;                     const f32x2 t = g2 * rl; f32x2 e; e.x = __builtin_amdgcn_exp2f(t.x); e.y = __builtin_amdgcn_exp2f(t.y);
;                     const f32x2 d = e + 1.0f; f32x2 rc; rc.x = __builtin_amdgcn_rcpf(d.x); rc.y = __builtin_amdgcn_rcpf(d.y);
;                     const f32x2 hv = ((g2 * u2) * r2) * rc;
;                     hw[q] = pk2(hv.x, hv.y);
;                 }
;                 u32x4 w; w.x = hw[0]; w.y = hw[1]; w.z = hw[2]; w.w = hw[3];
;                 *(u32x4*)(H + (size_t)(row0 + ai * 128 + m * 16) * DFF + col0) = w;
	v_pk_mul_f32 v[30:31], v[30:31], v[178:179] op_sel_hi:[1,0]
	v_exp_f32_e32 v41, v41
	v_cvt_pk_bf16_f32 v46, v42, v43
	v_pk_mul_f32 v[44:45], v[44:45], v[48:49]
	v_rcp_f32_e32 v38, v38
	v_pk_add_f32 v[40:41], v[40:41], 1.0 op_sel_hi:[1,0]
	v_rcp_f32_e32 v39, v39
	v_mul_f32_e32 v132, v131, v131
	v_pk_mul_f32 v[26:27], v[26:27], v[132:133] op_sel_hi:[1,0]
	v_exp_f32_e32 v30, v30
	v_pk_mul_f32 v[32:33], v[32:33], v[178:179] op_sel_hi:[1,0]
	v_exp_f32_e32 v31, v31
	v_cvt_pk_bf16_f32 v47, v44, v45
	v_pk_mul_f32 v[34:35], v[34:35], v[38:39]
	v_rcp_f32_e32 v40, v40
	v_pk_add_f32 v[30:31], v[30:31], 1.0 op_sel_hi:[1,0]
	v_rcp_f32_e32 v41, v41
	v_pk_mul_f32 v[28:29], v[28:29], v[132:133] op_sel_hi:[1,0]
	v_exp_f32_e32 v32, v32
	v_pk_mul_f32 v[22:23], v[22:23], v[178:179] op_sel_hi:[1,0]
	v_exp_f32_e32 v33, v33
	v_cvt_pk_bf16_f32 v48, v34, v35
	v_pk_mul_f32 v[36:37], v[36:37], v[40:41]
	v_rcp_f32_e32 v30, v30
	v_pk_add_f32 v[32:33], v[32:33], 1.0 op_sel_hi:[1,0]
	v_rcp_f32_e32 v31, v31
	v_pk_mul_f32 v[18:19], v[18:19], v[132:133] op_sel_hi:[1,0]
	v_exp_f32_e32 v22, v22
	v_pk_mul_f32 v[24:25], v[24:25], v[178:179] op_sel_hi:[1,0]
	v_exp_f32_e32 v23, v23
	v_cvt_pk_bf16_f32 v49, v36, v37
	v_mad_i64_i32 v[38:39], s[2:3], v150, s27, v[236:237]
	v_lshl_add_u64 v[38:39], v[38:39], 0, v[180:181]
	global_store_dwordx4 v[38:39], v[46:49], off
	v_pk_mul_f32 v[26:27], v[26:27], v[30:31]
	v_rcp_f32_e32 v32, v32
	v_pk_add_f32 v[22:23], v[22:23], 1.0 op_sel_hi:[1,0]
	v_rcp_f32_e32 v33, v33
	v_pk_mul_f32 v[20:21], v[20:21], v[132:133] op_sel_hi:[1,0]
	v_exp_f32_e32 v24, v24
	v_mul_f32_e32 v190, 0xbfb8aa3b, v130
	v_pk_mul_f32 v[14:15], v[14:15], v[190:191] op_sel_hi:[1,0]
	v_exp_f32_e32 v25, v25
	v_cvt_pk_bf16_f32 v30, v26, v27
	v_pk_mul_f32 v[28:29], v[28:29], v[32:33]
	v_rcp_f32_e32 v22, v22
	v_pk_add_f32 v[24:25], v[24:25], 1.0 op_sel_hi:[1,0]
	v_rcp_f32_e32 v23, v23
	v_mul_f32_e32 v234, v130, v130
	v_pk_mul_f32 v[10:11], v[10:11], v[234:235] op_sel_hi:[1,0]
	v_exp_f32_e32 v14, v14
	v_pk_mul_f32 v[16:17], v[16:17], v[190:191] op_sel_hi:[1,0]
	v_exp_f32_e32 v15, v15
	v_cvt_pk_bf16_f32 v31, v28, v29
	v_pk_mul_f32 v[18:19], v[18:19], v[22:23]
	v_rcp_f32_e32 v24, v24
	v_pk_add_f32 v[14:15], v[14:15], 1.0 op_sel_hi:[1,0]
	v_rcp_f32_e32 v25, v25
	v_pk_mul_f32 v[12:13], v[12:13], v[234:235] op_sel_hi:[1,0]
	v_exp_f32_e32 v16, v16
	v_pk_mul_f32 v[6:7], v[6:7], v[190:191] op_sel_hi:[1,0]
	v_exp_f32_e32 v17, v17
	v_cvt_pk_bf16_f32 v32, v18, v19
	v_pk_mul_f32 v[20:21], v[20:21], v[24:25]
	v_rcp_f32_e32 v14, v14
	v_pk_add_f32 v[16:17], v[16:17], 1.0 op_sel_hi:[1,0]
	v_rcp_f32_e32 v15, v15
	v_pk_mul_f32 v[2:3], v[2:3], v[234:235] op_sel_hi:[1,0]
	v_exp_f32_e32 v6, v6
	v_pk_mul_f32 v[8:9], v[8:9], v[190:191] op_sel_hi:[1,0]
	v_exp_f32_e32 v7, v7
	v_cvt_pk_bf16_f32 v33, v20, v21
	v_mad_i64_i32 v[22:23], s[2:3], v148, s27, v[236:237]
	v_lshl_add_u64 v[22:23], v[22:23], 0, v[180:181]
	global_store_dwordx4 v[22:23], v[30:33], off
	v_pk_mul_f32 v[10:11], v[10:11], v[14:15]
	v_rcp_f32_e32 v16, v16
	v_pk_add_f32 v[6:7], v[6:7], 1.0 op_sel_hi:[1,0]
	v_rcp_f32_e32 v17, v17
	v_pk_mul_f32 v[4:5], v[4:5], v[234:235] op_sel_hi:[1,0]
	v_exp_f32_e32 v8, v8
	v_exp_f32_e32 v9, v9
	v_cvt_pk_bf16_f32 v14, v10, v11
	v_pk_mul_f32 v[12:13], v[12:13], v[16:17]
	v_rcp_f32_e32 v6, v6
	v_pk_add_f32 v[8:9], v[8:9], 1.0 op_sel_hi:[1,0]
	v_rcp_f32_e32 v7, v7
	v_cvt_pk_bf16_f32 v15, v12, v13
	v_pk_mul_f32 v[2:3], v[2:3], v[6:7]
	v_rcp_f32_e32 v8, v8
	v_rcp_f32_e32 v9, v9
	v_cvt_pk_bf16_f32 v16, v2, v3
	v_pk_mul_f32 v[4:5], v[4:5], v[8:9]
	v_cvt_pk_bf16_f32 v17, v4, v5
	v_mad_i64_i32 v[6:7], s[2:3], v146, s27, v[236:237]
	v_lshl_add_u64 v[6:7], v[6:7], 0, v[180:181]
	global_store_dwordx4 v[6:7], v[14:17], off
	s_andn2_b64 vcc, exec, s[40:41]
	s_mov_b64 s[2:3], -1
	s_cbranch_vccnz .LBB0_162
	s_andn2_b64 vcc, exec, s[38:39]
	s_cbranch_vccnz .LBB0_161
	s_barrier
	s_branch .LBB0_161

; DI unsigned pk2(float lo, float hi) { return pg8::cvt_pk_bf16(lo, hi); }
;     DI void operator()(const f32x4 (&acc)[2][2][4][2], const pg8::Unit& u, int wr, int wc, int fr, int fq) const {
;     ...
; #pragma unroll
;         for (int ai = 0; ai < 2; ++ai)
; #pragma unroll
;             for (int m = 0; m < 4; ++m) {
;                 typedef float f32x2 __attribute__((ext_vector_type(2)));
;                 const float r = rs[ai][m]; const float r2s = r * r, rls = r * -1.44269504f; const f32x2 r2 = {r2s, r2s}, rl = {rls, rls};
;                 unsigned hw[4];
; #pragma unroll
;                 for (int q = 0; q < 4; ++q) {
;                     const f32x4 gq = acc[ai][0][m][q >> 1], uq = acc[ai][1][m][q >> 1];
;                     const f32x2 g2 = {gq[2 * (q & 1)], gq[2 * (q & 1) + 1]}, u2 = {uq[2 * (q & 1)], uq[2 * (q & 1) + 1]};
;                     const f32x2 t = g2 * rl; f32x2 e; e.x = __builtin_amdgcn_exp2f(t.x); e.y = __builtin_amdgcn_exp2f(t.y);
;                     const f32x2 d = e + 1.0f; f32x2 rc; rc.x = __builtin_amdgcn_rcpf(d.x); rc.y = __builtin_amdgcn_rcpf(d.y);
;                     const f32x2 hv = ((g2 * u2) * r2) * rc;
;                     hw[q] = pk2(hv.x, hv.y);
;                 }
;                 u32x4 w; w.x = hw[0]; w.y = hw[1]; w.z = hw[2]; w.w = hw[3];
;                 *(u32x4*)(H + (size_t)(row0 + ai * 128 + m * 16) * DFF + col0) = w;
.Lrc_done_1:
	v_mov_b64_e32 v[236:237], s[84:85]
	v_lshlrev_b64 v[180:181], 1, v[162:163]
	v_mul_f32_e32 v178, 0xbfb8aa3b, v161
	v_pk_mul_f32 v[126:127], v[126:127], v[178:179] op_sel_hi:[1,0]
	v_mul_f32_e32 v132, v161, v161
	v_pk_mul_f32 v[122:123], v[122:123], v[132:133] op_sel_hi:[1,0]
	v_exp_f32_e32 v126, v126
	v_pk_mul_f32 v[128:129], v[128:129], v[178:179] op_sel_hi:[1,0]
	v_exp_f32_e32 v127, v127
	s_nop 0
	v_pk_add_f32 v[126:127], v[126:127], 1.0 op_sel_hi:[1,0]
	v_pk_mul_f32 v[124:125], v[124:125], v[132:133] op_sel_hi:[1,0]
	v_exp_f32_e32 v128, v128
	v_pk_mul_f32 v[118:119], v[118:119], v[178:179] op_sel_hi:[1,0]
	v_exp_f32_e32 v129, v129
	v_rcp_f32_e32 v126, v126
	v_pk_add_f32 v[128:129], v[128:129], 1.0 op_sel_hi:[1,0]
	v_rcp_f32_e32 v127, v127
	v_pk_mul_f32 v[114:115], v[114:115], v[132:133] op_sel_hi:[1,0]
	v_exp_f32_e32 v118, v118
	v_pk_mul_f32 v[120:121], v[120:121], v[178:179] op_sel_hi:[1,0]
	v_exp_f32_e32 v119, v119
	v_pk_mul_f32 v[122:123], v[122:123], v[126:127]
	v_rcp_f32_e32 v128, v128
	v_pk_add_f32 v[118:119], v[118:119], 1.0 op_sel_hi:[1,0]
	v_rcp_f32_e32 v129, v129
	v_pk_mul_f32 v[116:117], v[116:117], v[132:133] op_sel_hi:[1,0]
	v_exp_f32_e32 v120, v120
	v_mul_f32_e32 v190, 0xbfb8aa3b, v159
	v_pk_mul_f32 v[110:111], v[110:111], v[190:191] op_sel_hi:[1,0]
	v_exp_f32_e32 v121, v121
	v_cvt_pk_bf16_f32 v126, v122, v123
	v_pk_mul_f32 v[124:125], v[124:125], v[128:129]
	v_rcp_f32_e32 v118, v118
	v_pk_add_f32 v[120:121], v[120:121], 1.0 op_sel_hi:[1,0]
	v_rcp_f32_e32 v119, v119
	v_mul_f32_e32 v234, v159, v159
	v_pk_mul_f32 v[106:107], v[106:107], v[234:235] op_sel_hi:[1,0]
	v_exp_f32_e32 v110, v110
	v_pk_mul_f32 v[112:113], v[112:113], v[190:191] op_sel_hi:[1,0]
	v_exp_f32_e32 v111, v111
	v_cvt_pk_bf16_f32 v127, v124, v125
	v_pk_mul_f32 v[114:115], v[114:115], v[118:119]
	v_rcp_f32_e32 v120, v120
	v_pk_add_f32 v[110:111], v[110:111], 1.0 op_sel_hi:[1,0]
	v_rcp_f32_e32 v121, v121
	v_pk_mul_f32 v[108:109], v[108:109], v[234:235] op_sel_hi:[1,0]
	v_exp_f32_e32 v112, v112
	v_pk_mul_f32 v[102:103], v[102:103], v[190:191] op_sel_hi:[1,0]
	v_exp_f32_e32 v113, v113
	v_cvt_pk_bf16_f32 v128, v114, v115
	v_pk_mul_f32 v[116:117], v[116:117], v[120:121]
	v_rcp_f32_e32 v110, v110
	v_pk_add_f32 v[112:113], v[112:113], 1.0 op_sel_hi:[1,0]
	v_rcp_f32_e32 v111, v111
	v_pk_mul_f32 v[98:99], v[98:99], v[234:235] op_sel_hi:[1,0]
	v_exp_f32_e32 v102, v102
	v_pk_mul_f32 v[104:105], v[104:105], v[190:191] op_sel_hi:[1,0]
	v_exp_f32_e32 v103, v103
	v_cvt_pk_bf16_f32 v129, v116, v117
	v_mad_i64_i32 v[118:119], s[2:3], v160, s27, v[236:237]
	v_lshl_add_u64 v[118:119], v[118:119], 0, v[180:181]
	global_store_dwordx4 v[118:119], v[126:129], off
	v_pk_mul_f32 v[106:107], v[106:107], v[110:111]
	v_rcp_f32_e32 v112, v112
	v_pk_add_f32 v[102:103], v[102:103], 1.0 op_sel_hi:[1,0]
	v_rcp_f32_e32 v113, v113
	v_pk_mul_f32 v[100:101], v[100:101], v[234:235] op_sel_hi:[1,0]
	v_exp_f32_e32 v104, v104
	v_mul_f32_e32 v178, 0xbfb8aa3b, v157
	v_pk_mul_f32 v[94:95], v[94:95], v[178:179] op_sel_hi:[1,0]
	v_exp_f32_e32 v105, v105
	v_cvt_pk_bf16_f32 v110, v106, v107
	v_pk_mul_f32 v[108:109], v[108:109], v[112:113]
	v_rcp_f32_e32 v102, v102
	v_pk_add_f32 v[104:105], v[104:105], 1.0 op_sel_hi:[1,0]
	v_rcp_f32_e32 v103, v103
	v_mul_f32_e32 v132, v157, v157
	v_pk_mul_f32 v[90:91], v[90:91], v[132:133] op_sel_hi:[1,0]
	v_exp_f32_e32 v94, v94
	v_pk_mul_f32 v[96:97], v[96:97], v[178:179] op_sel_hi:[1,0]
	v_exp_f32_e32 v95, v95
	v_cvt_pk_bf16_f32 v111, v108, v109
	v_pk_mul_f32 v[98:99], v[98:99], v[102:103]
	v_rcp_f32_e32 v104, v104
	v_pk_add_f32 v[94:95], v[94:95], 1.0 op_sel_hi:[1,0]
	v_rcp_f32_e32 v105, v105
	v_pk_mul_f32 v[92:93], v[92:93], v[132:133] op_sel_hi:[1,0]
	v_exp_f32_e32 v96, v96
	v_pk_mul_f32 v[86:87], v[86:87], v[178:179] op_sel_hi:[1,0]
	v_exp_f32_e32 v97, v97
	v_cvt_pk_bf16_f32 v112, v98, v99
	v_pk_mul_f32 v[100:101], v[100:101], v[104:105]
	v_rcp_f32_e32 v94, v94
	v_pk_add_f32 v[96:97], v[96:97], 1.0 op_sel_hi:[1,0]
	v_rcp_f32_e32 v95, v95
	v_pk_mul_f32 v[82:83], v[82:83], v[132:133] op_sel_hi:[1,0]
	v_exp_f32_e32 v86, v86
	v_pk_mul_f32 v[88:89], v[88:89], v[178:179] op_sel_hi:[1,0]
	v_exp_f32_e32 v87, v87
	v_cvt_pk_bf16_f32 v113, v100, v101
	v_mad_i64_i32 v[102:103], s[2:3], v158, s27, v[236:237]
	v_lshl_add_u64 v[102:103], v[102:103], 0, v[180:181]
	global_store_dwordx4 v[102:103], v[110:113], off
	v_pk_mul_f32 v[90:91], v[90:91], v[94:95]
	v_rcp_f32_e32 v96, v96
	v_pk_add_f32 v[86:87], v[86:87], 1.0 op_sel_hi:[1,0]
	v_rcp_f32_e32 v97, v97
	v_pk_mul_f32 v[84:85], v[84:85], v[132:133] op_sel_hi:[1,0]
	v_exp_f32_e32 v88, v88
	v_mul_f32_e32 v190, 0xbfb8aa3b, v155
	v_pk_mul_f32 v[78:79], v[78:79], v[190:191] op_sel_hi:[1,0]
	v_exp_f32_e32 v89, v89
	v_cvt_pk_bf16_f32 v94, v90, v91
	v_pk_mul_f32 v[92:93], v[92:93], v[96:97]
	v_rcp_f32_e32 v86, v86
	v_pk_add_f32 v[88:89], v[88:89], 1.0 op_sel_hi:[1,0]
	v_rcp_f32_e32 v87, v87
	v_mul_f32_e32 v234, v155, v155
	v_pk_mul_f32 v[74:75], v[74:75], v[234:235] op_sel_hi:[1,0]
	v_exp_f32_e32 v78, v78
	v_pk_mul_f32 v[80:81], v[80:81], v[190:191] op_sel_hi:[1,0]
	v_exp_f32_e32 v79, v79
	v_cvt_pk_bf16_f32 v95, v92, v93
	v_pk_mul_f32 v[82:83], v[82:83], v[86:87]
	v_rcp_f32_e32 v88, v88
	v_pk_add_f32 v[78:79], v[78:79], 1.0 op_sel_hi:[1,0]
	v_rcp_f32_e32 v89, v89
	v_pk_mul_f32 v[76:77], v[76:77], v[234:235] op_sel_hi:[1,0]
	v_exp_f32_e32 v80, v80
	v_pk_mul_f32 v[70:71], v[70:71], v[190:191] op_sel_hi:[1,0]
	v_exp_f32_e32 v81, v81
	v_cvt_pk_bf16_f32 v96, v82, v83
	v_pk_mul_f32 v[84:85], v[84:85], v[88:89]
	v_rcp_f32_e32 v78, v78
	v_pk_add_f32 v[80:81], v[80:81], 1.0 op_sel_hi:[1,0]
	v_rcp_f32_e32 v79, v79
; DI unsigned pk2(float lo, float hi) { return pg8::cvt_pk_bf16(lo, hi); }
;     DI void operator()(const f32x4 (&acc)[2][2][4][2], const pg8::Unit& u, int wr, int wc, int fr, int fq) const {
;     ...
; #pragma unroll
;         for (int ai = 0; ai < 2; ++ai)
; #pragma unroll
;             for (int m = 0; m < 4; ++m) {
;                 typedef float f32x2 __attribute__((ext_vector_type(2)));
;                 const float r = rs[ai][m]; const float r2s = r * r, rls = r * -1.44269504f; const f32x2 r2 = {r2s, r2s}, rl = {rls, rls};
;                 unsigned hw[4];
; #pragma unroll
;                 for (int q = 0; q < 4; ++q) {
;                     const f32x4 gq = acc[ai][0][m][q >> 1], uq = acc[ai][1][m][q >> 1];
;                     const f32x2 g2 = {gq[2 * (q & 1)], gq[2 * (q & 1) + 1]}, u2 = {uq[2 * (q & 1)], uq[2 * (q & 1) + 1]};
;                     const f32x2 t = g2 * rl; f32x2 e; e.x = __builtin_amdgcn_exp2f(t.x); e.y = __builtin_amdgcn_exp2f(t.y);
;                     const f32x2 d = e + 1.0f; f32x2 rc; rc.x = __builtin_amdgcn_rcpf(d.x); rc.y = __builtin_amdgcn_rcpf(d.y);
;                     const f32x2 hv = ((g2 * u2) * r2) * rc;
;                     hw[q] = pk2(hv.x, hv.y);
;                 }
;                 u32x4 w; w.x = hw[0]; w.y = hw[1]; w.z = hw[2]; w.w = hw[3];
;                 *(u32x4*)(H + (size_t)(row0 + ai * 128 + m * 16) * DFF + col0) = w;
	v_pk_mul_f32 v[66:67], v[66:67], v[234:235] op_sel_hi:[1,0]
	v_exp_f32_e32 v70, v70
	v_pk_mul_f32 v[72:73], v[72:73], v[190:191] op_sel_hi:[1,0]
	v_exp_f32_e32 v71, v71
	v_cvt_pk_bf16_f32 v97, v84, v85
	v_mad_i64_i32 v[86:87], s[2:3], v156, s27, v[236:237]
	v_lshl_add_u64 v[86:87], v[86:87], 0, v[180:181]
	global_store_dwordx4 v[86:87], v[94:97], off
	v_pk_mul_f32 v[74:75], v[74:75], v[78:79]
	v_rcp_f32_e32 v80, v80
	v_pk_add_f32 v[70:71], v[70:71], 1.0 op_sel_hi:[1,0]
	v_rcp_f32_e32 v81, v81
	v_pk_mul_f32 v[68:69], v[68:69], v[234:235] op_sel_hi:[1,0]
	v_exp_f32_e32 v72, v72
	v_mul_f32_e32 v178, 0xbfb8aa3b, v153
	v_pk_mul_f32 v[62:63], v[62:63], v[178:179] op_sel_hi:[1,0]
	v_exp_f32_e32 v73, v73
	v_cvt_pk_bf16_f32 v78, v74, v75
	v_pk_mul_f32 v[76:77], v[76:77], v[80:81]
	v_rcp_f32_e32 v70, v70
	v_pk_add_f32 v[72:73], v[72:73], 1.0 op_sel_hi:[1,0]
	v_rcp_f32_e32 v71, v71
	v_mul_f32_e32 v132, v153, v153
	v_pk_mul_f32 v[58:59], v[58:59], v[132:133] op_sel_hi:[1,0]
	v_exp_f32_e32 v62, v62
	v_pk_mul_f32 v[64:65], v[64:65], v[178:179] op_sel_hi:[1,0]
	v_exp_f32_e32 v63, v63
	v_cvt_pk_bf16_f32 v79, v76, v77
	v_pk_mul_f32 v[66:67], v[66:67], v[70:71]
	v_rcp_f32_e32 v72, v72
	v_pk_add_f32 v[62:63], v[62:63], 1.0 op_sel_hi:[1,0]
	v_rcp_f32_e32 v73, v73
	v_pk_mul_f32 v[60:61], v[60:61], v[132:133] op_sel_hi:[1,0]
	v_exp_f32_e32 v64, v64
	v_pk_mul_f32 v[54:55], v[54:55], v[178:179] op_sel_hi:[1,0]
	v_exp_f32_e32 v65, v65
	v_cvt_pk_bf16_f32 v80, v66, v67
	v_pk_mul_f32 v[68:69], v[68:69], v[72:73]
	v_rcp_f32_e32 v62, v62
	v_pk_add_f32 v[64:65], v[64:65], 1.0 op_sel_hi:[1,0]
	v_rcp_f32_e32 v63, v63
	v_pk_mul_f32 v[50:51], v[50:51], v[132:133] op_sel_hi:[1,0]
	v_exp_f32_e32 v54, v54
	v_pk_mul_f32 v[56:57], v[56:57], v[178:179] op_sel_hi:[1,0]
	v_exp_f32_e32 v55, v55
	v_cvt_pk_bf16_f32 v81, v68, v69
	v_mad_i64_i32 v[70:71], s[2:3], v154, s27, v[236:237]
	v_lshl_add_u64 v[70:71], v[70:71], 0, v[180:181]
	global_store_dwordx4 v[70:71], v[78:81], off
	v_pk_mul_f32 v[58:59], v[58:59], v[62:63]
	v_rcp_f32_e32 v64, v64
	v_pk_add_f32 v[54:55], v[54:55], 1.0 op_sel_hi:[1,0]
	v_rcp_f32_e32 v65, v65
	v_pk_mul_f32 v[52:53], v[52:53], v[132:133] op_sel_hi:[1,0]
	v_exp_f32_e32 v56, v56
	v_mul_f32_e32 v190, 0xbfb8aa3b, v151
	v_pk_mul_f32 v[46:47], v[46:47], v[190:191] op_sel_hi:[1,0]
	v_exp_f32_e32 v57, v57
	v_cvt_pk_bf16_f32 v62, v58, v59
	v_pk_mul_f32 v[60:61], v[60:61], v[64:65]
	v_rcp_f32_e32 v54, v54
	v_pk_add_f32 v[56:57], v[56:57], 1.0 op_sel_hi:[1,0]
	v_rcp_f32_e32 v55, v55
	v_mul_f32_e32 v234, v151, v151
	v_pk_mul_f32 v[42:43], v[42:43], v[234:235] op_sel_hi:[1,0]
	v_exp_f32_e32 v46, v46
	v_pk_mul_f32 v[48:49], v[48:49], v[190:191] op_sel_hi:[1,0]
	v_exp_f32_e32 v47, v47
	v_cvt_pk_bf16_f32 v63, v60, v61
	v_pk_mul_f32 v[50:51], v[50:51], v[54:55]
	v_rcp_f32_e32 v56, v56
	v_pk_add_f32 v[46:47], v[46:47], 1.0 op_sel_hi:[1,0]
	v_rcp_f32_e32 v57, v57
	v_pk_mul_f32 v[44:45], v[44:45], v[234:235] op_sel_hi:[1,0]
	v_exp_f32_e32 v48, v48
	v_pk_mul_f32 v[38:39], v[38:39], v[190:191] op_sel_hi:[1,0]
	v_exp_f32_e32 v49, v49
	v_cvt_pk_bf16_f32 v64, v50, v51
	v_pk_mul_f32 v[52:53], v[52:53], v[56:57]
	v_rcp_f32_e32 v46, v46
	v_pk_add_f32 v[48:49], v[48:49], 1.0 op_sel_hi:[1,0]
	v_rcp_f32_e32 v47, v47
	v_pk_mul_f32 v[34:35], v[34:35], v[234:235] op_sel_hi:[1,0]
	v_exp_f32_e32 v38, v38
	v_pk_mul_f32 v[40:41], v[40:41], v[190:191] op_sel_hi:[1,0]
	v_exp_f32_e32 v39, v39
	v_cvt_pk_bf16_f32 v65, v52, v53
	v_mad_i64_i32 v[54:55], s[2:3], v152, s27, v[236:237]
	v_lshl_add_u64 v[54:55], v[54:55], 0, v[180:181]
	global_store_dwordx4 v[54:55], v[62:65], off
	v_pk_mul_f32 v[42:43], v[42:43], v[46:47]
	v_rcp_f32_e32 v48, v48
	v_pk_add_f32 v[38:39], v[38:39], 1.0 op_sel_hi:[1,0]
	v_rcp_f32_e32 v49, v49
	v_pk_mul_f32 v[36:37], v[36:37], v[234:235] op_sel_hi:[1,0]
	v_exp_f32_e32 v40, v40
	v_mul_f32_e32 v178, 0xbfb8aa3b, v131
; #define PG8_BAR __builtin_amdgcn_s_barrier()
; DI unsigned pk2(float lo, float hi) { return pg8::cvt_pk_bf16(lo, hi); }
; template <class Epi, class Sched, bool ALIGN_EPI = false, bool SP2 = false>
; __device__ __forceinline__ void gemm_phase(PG8_LAS unsigned char* lds, const Gemm g, const Sched& S, const Epi& E) {
;     ...
;         if constexpr (ALIGN_EPI) { if (wr == 0) PG8_BAR; }
;         if constexpr (!Epi::AFTER_DRAIN) { E(acc, cur, wr, wc, fr, fq); S.done(cur); }
;         if (!has_next) break;
; #pragma unroll
;         for (int a = 0; a < 2; ++a)
; #pragma unroll
;             for (int b = 0; b < 2; ++b)
; #pragma unroll
;                 for (int m = 0; m < 4; ++m)
; #pragma unroll
;                     for (int n = 0; n < 2; ++n) acc[a][b][m][n] = (f32x4){0.f, 0.f, 0.f, 0.f};
;         cur = nxt; cA = nA; cB = nB; ++ui;
;         if constexpr (ALIGN_EPI) { if (wr == 1) PG8_BAR; }
;     DI void operator()(const f32x4 (&acc)[2][2][4][2], const pg8::Unit& u, int wr, int wc, int fr, int fq) const {
;     ...
; #pragma unroll
;         for (int ai = 0; ai < 2; ++ai)
; #pragma unroll
;             for (int m = 0; m < 4; ++m) {
;                 typedef float f32x2 __attribute__((ext_vector_type(2)));
;                 const float r = rs[ai][m]; const float r2s = r * r, rls = r * -1.44269504f; const f32x2 r2 = {r2s, r2s}, rl = {rls, rls};
;                 unsigned hw[4];
; #pragma unroll
;                 for (int q = 0; q < 4; ++q) {
;                     const f32x4 gq = acc[ai][0][m][q >> 1], uq = acc[ai][1][m][q >> 1];
;                     const f32x2 g2 = {gq[2 * (q & 1)], gq[2 * (q & 1) + 1]}, u2 = {uq[2 * (q & 1)], uq[2 * (q & 1) + 1]};
;                     const f32x2 t = g2 * rl; f32x2 e; e.x = __builtin_amdgcn_exp2f(t.x); e.y = __builtin_amdgcn_exp2f(t.y);
;                     const f32x2 d = e + 1.0f; f32x2 rc; rc.x = __builtin_amdgcn_rcpf(d.x); rc.y = __builtin_amdgcn_rcpf(d.y);
;                     const f32x2 hv = ((g2 * u2) * r2) * rc;
;                     hw[q] = pk2(hv.x, hv.y);
;                 }
;                 u32x4 w; w.x = hw[0]; w.y = hw[1]; w.z = hw[2]; w.w = hw[3];
;                 *(u32x4*)(H + (size_t)(row0 + ai * 128 + m * 16) * DFF + col0) = w;
	v_pk_mul_f32 v[30:31], v[30:31], v[178:179] op_sel_hi:[1,0]
	v_exp_f32_e32 v41, v41
	v_cvt_pk_bf16_f32 v46, v42, v43
	v_pk_mul_f32 v[44:45], v[44:45], v[48:49]
	v_rcp_f32_e32 v38, v38
	v_pk_add_f32 v[40:41], v[40:41], 1.0 op_sel_hi:[1,0]
	v_rcp_f32_e32 v39, v39
	v_mul_f32_e32 v132, v131, v131
	v_pk_mul_f32 v[26:27], v[26:27], v[132:133] op_sel_hi:[1,0]
	v_exp_f32_e32 v30, v30
	v_pk_mul_f32 v[32:33], v[32:33], v[178:179] op_sel_hi:[1,0]
	v_exp_f32_e32 v31, v31
	v_cvt_pk_bf16_f32 v47, v44, v45
	v_pk_mul_f32 v[34:35], v[34:35], v[38:39]
	v_rcp_f32_e32 v40, v40
	v_pk_add_f32 v[30:31], v[30:31], 1.0 op_sel_hi:[1,0]
	v_rcp_f32_e32 v41, v41
	v_pk_mul_f32 v[28:29], v[28:29], v[132:133] op_sel_hi:[1,0]
	v_exp_f32_e32 v32, v32
	v_pk_mul_f32 v[22:23], v[22:23], v[178:179] op_sel_hi:[1,0]
	v_exp_f32_e32 v33, v33
	v_cvt_pk_bf16_f32 v48, v34, v35
	v_pk_mul_f32 v[36:37], v[36:37], v[40:41]
	v_rcp_f32_e32 v30, v30
	v_pk_add_f32 v[32:33], v[32:33], 1.0 op_sel_hi:[1,0]
	v_rcp_f32_e32 v31, v31
	v_pk_mul_f32 v[18:19], v[18:19], v[132:133] op_sel_hi:[1,0]
	v_exp_f32_e32 v22, v22
	v_pk_mul_f32 v[24:25], v[24:25], v[178:179] op_sel_hi:[1,0]
	v_exp_f32_e32 v23, v23
	v_cvt_pk_bf16_f32 v49, v36, v37
	v_mad_i64_i32 v[38:39], s[2:3], v150, s27, v[236:237]
	v_lshl_add_u64 v[38:39], v[38:39], 0, v[180:181]
	global_store_dwordx4 v[38:39], v[46:49], off
	v_pk_mul_f32 v[26:27], v[26:27], v[30:31]
	v_rcp_f32_e32 v32, v32
	v_pk_add_f32 v[22:23], v[22:23], 1.0 op_sel_hi:[1,0]
	v_rcp_f32_e32 v33, v33
	v_pk_mul_f32 v[20:21], v[20:21], v[132:133] op_sel_hi:[1,0]
	v_exp_f32_e32 v24, v24
	v_mul_f32_e32 v190, 0xbfb8aa3b, v130
	v_pk_mul_f32 v[14:15], v[14:15], v[190:191] op_sel_hi:[1,0]
	v_exp_f32_e32 v25, v25
	v_cvt_pk_bf16_f32 v30, v26, v27
	v_pk_mul_f32 v[28:29], v[28:29], v[32:33]
	v_rcp_f32_e32 v22, v22
	v_pk_add_f32 v[24:25], v[24:25], 1.0 op_sel_hi:[1,0]
	v_rcp_f32_e32 v23, v23
	v_mul_f32_e32 v234, v130, v130
	v_pk_mul_f32 v[10:11], v[10:11], v[234:235] op_sel_hi:[1,0]
	v_exp_f32_e32 v14, v14
	v_pk_mul_f32 v[16:17], v[16:17], v[190:191] op_sel_hi:[1,0]
	v_exp_f32_e32 v15, v15
	v_cvt_pk_bf16_f32 v31, v28, v29
	v_pk_mul_f32 v[18:19], v[18:19], v[22:23]
	v_rcp_f32_e32 v24, v24
	v_pk_add_f32 v[14:15], v[14:15], 1.0 op_sel_hi:[1,0]
	v_rcp_f32_e32 v25, v25
	v_pk_mul_f32 v[12:13], v[12:13], v[234:235] op_sel_hi:[1,0]
	v_exp_f32_e32 v16, v16
	v_pk_mul_f32 v[6:7], v[6:7], v[190:191] op_sel_hi:[1,0]
	v_exp_f32_e32 v17, v17
	v_cvt_pk_bf16_f32 v32, v18, v19
	v_pk_mul_f32 v[20:21], v[20:21], v[24:25]
	v_rcp_f32_e32 v14, v14
	v_pk_add_f32 v[16:17], v[16:17], 1.0 op_sel_hi:[1,0]
	v_rcp_f32_e32 v15, v15
	v_pk_mul_f32 v[2:3], v[2:3], v[234:235] op_sel_hi:[1,0]
	v_exp_f32_e32 v6, v6
	v_pk_mul_f32 v[8:9], v[8:9], v[190:191] op_sel_hi:[1,0]
	v_exp_f32_e32 v7, v7
	v_cvt_pk_bf16_f32 v33, v20, v21
	v_mad_i64_i32 v[22:23], s[2:3], v148, s27, v[236:237]
	v_lshl_add_u64 v[22:23], v[22:23], 0, v[180:181]
	global_store_dwordx4 v[22:23], v[30:33], off
	v_pk_mul_f32 v[10:11], v[10:11], v[14:15]
	v_rcp_f32_e32 v16, v16
	v_pk_add_f32 v[6:7], v[6:7], 1.0 op_sel_hi:[1,0]
	v_rcp_f32_e32 v17, v17
	v_pk_mul_f32 v[4:5], v[4:5], v[234:235] op_sel_hi:[1,0]
	v_exp_f32_e32 v8, v8
	v_exp_f32_e32 v9, v9
	v_cvt_pk_bf16_f32 v14, v10, v11
	v_pk_mul_f32 v[12:13], v[12:13], v[16:17]
	v_rcp_f32_e32 v6, v6
	v_pk_add_f32 v[8:9], v[8:9], 1.0 op_sel_hi:[1,0]
	v_rcp_f32_e32 v7, v7
	v_cvt_pk_bf16_f32 v15, v12, v13
	v_pk_mul_f32 v[2:3], v[2:3], v[6:7]
	v_rcp_f32_e32 v8, v8
	v_rcp_f32_e32 v9, v9
	v_cvt_pk_bf16_f32 v16, v2, v3
	v_pk_mul_f32 v[4:5], v[4:5], v[8:9]
	v_cvt_pk_bf16_f32 v17, v4, v5
	v_mad_i64_i32 v[6:7], s[2:3], v146, s27, v[236:237]
	v_lshl_add_u64 v[6:7], v[6:7], 0, v[180:181]
	global_store_dwordx4 v[6:7], v[14:17], off
	s_andn2_b64 vcc, exec, s[38:39]
	s_mov_b64 s[2:3], -1
	s_cbranch_vccnz .LBB0_1118
	s_andn2_b64 vcc, exec, s[42:43]
	s_cbranch_vccnz .LBB0_1117
	s_barrier
	s_branch .LBB0_1117
